# P2: half of the workgroups (bit 3 of the block id, id>=48) run the pooling units before their conv tile, so the bandwidth-bound conv of one half overlaps the latency-bound pooling of the other
# speedup vs baseline: 1.0064x; 1.0025x over previous
; #define CONV_F(dst, x, c) do { dst[0] = bflo(x.x) * bflo(c.x); dst[1] = bfhi(x.x) * bfhi(c.x); dst[2] = bflo(x.y) * bflo(c.y); dst[3] = bfhi(x.y) * bfhi(c.y); \
;     dst[4] = bflo(x.z) * bflo(c.z); dst[5] = bfhi(x.z) * bfhi(c.z); dst[6] = bflo(x.w) * bflo(c.w); dst[7] = bfhi(x.w) * bfhi(c.w); } while (0)
; __device__ __forceinline__ void mixer_phase(const Params& p, LAS unsigned char* lds) {
;     ...
;     for (int tt = bx; tt < 256; tt += G) {
;         const int b = tt >> 5, t0 = (tt & 31) * 64;
;         const int c8 = (tid & 63) * 8, ts = t0 + (tid >> 6) * 8;
;         float w0[8], w1[8], w2[8], f1[8], f2[8];
;         { const float* cw = p.in[10] + c8;
;             const f32x4 a0 = *(const f32x4*)(cw), a1 = *(const f32x4*)(cw + 4), b0 = *(const f32x4*)(cw + 512), b1 = *(const f32x4*)(cw + 516), c0 = *(const f32x4*)(cw + 1024), c1 = *(const f32x4*)(cw + 1028);
; #pragma unroll
;             for (int j = 0; j < 4; ++j) { w0[j] = a0[j]; w0[j + 4] = a1[j]; w1[j] = b0[j]; w1[j + 4] = b1[j]; w2[j] = c0[j]; w2[j + 4] = c1[j]; } }
; #pragma unroll
;         for (int j = 0; j < 8; ++j) { f1[j] = 0.f; f2[j] = 0.f; }
;         if (ts >= 2) { const bf16_t* zr = zb + (size_t)(b * T + ts - 2) * 2048; const u32x4 x = *(const u32x4*)(zr + 512 + c8), c = *(const u32x4*)(zr + 1536 + c8); CONV_F(f2, x, c); }
;         if (ts >= 1) { const bf16_t* zr = zb + (size_t)(b * T + ts - 1) * 2048; const u32x4 x = *(const u32x4*)(zr + 512 + c8), c = *(const u32x4*)(zr + 1536 + c8); CONV_F(f1, x, c); }
.LBB0_265:
.LBB0_266:
	s_mov_b32 s101, 0
	v_and_b32_e32 v90, 63, v0
	s_cmpk_gt_i32 s2, 0xff
	v_lshlrev_b32_e32 v108, 5, v90
	v_lshlrev_b32_e32 v106, 4, v90
	s_cbranch_scc1 .LBB0_287
	s_cmp_lg_u32 s3, 0x100
	s_cbranch_scc1 .Lmy_conv_body
	s_cmp_lt_u32 s2, 48
	s_cbranch_scc1 .Lmy_conv_body
	s_bitcmp1_b32 s2, 3
	s_cbranch_scc0 .Lmy_conv_body
	s_mov_b32 s101, 1
	s_branch .LBB0_287
.Lmy_conv_body:
	s_load_dwordx16 s[36:51], s[0:1], 0x40
	v_mov_b32_e32 v109, 0
	s_mov_b64 s[6:7], 0x1000
	v_lshl_add_u64 v[14:15], s[28:29], 0, v[108:109]
	v_mov_b32_e32 v107, v109
	s_waitcnt vmcnt(0) lgkmcnt(0)
	v_lshl_add_u64 v[50:51], s[40:41], 0, v[108:109]
	v_lshl_add_u64 v[52:53], v[50:51], 0, s[6:7]
	s_mov_b64 s[6:7], 0x447c000
	v_lshl_add_u64 v[54:55], v[14:15], 0, s[6:7]
	s_movk_i32 s6, 0xe000
	v_lshlrev_b32_e32 v91, 3, v1
	v_lshl_add_u64 v[56:57], s[64:65], 0, v[106:107]
	v_lshl_add_u64 v[58:59], s[66:67], 0, v[106:107]
	s_lshl_b32 s11, s2, 6
	s_lshl_b32 s12, s3, 6
	s_mov_b32 s7, -1
	s_movk_i32 s13, 0x7fd
	s_mov_b32 s52, s2
	s_branch .LBB0_269

; #define LAS __attribute__((address_space(3)))
; #define LDS_BARRIER() do { asm volatile("s_waitcnt lgkmcnt(0)" ::: "memory"); __builtin_amdgcn_s_barrier(); asm volatile("" ::: "memory"); } while (0)
; __device__ __forceinline__ bf16_t f2bf(float f) { unsigned u = __float_as_uint(f); u += 0x7FFFu + ((u >> 16) & 1u); return (bf16_t)(u >> 16); }
; __device__ __forceinline__ float bflo(unsigned u) { return __uint_as_float(u << 16); }
; __device__ __forceinline__ float bfhi(unsigned u) { return __uint_as_float(u & 0xffff0000u); }
; __device__ __forceinline__ void mixer_phase(const Params& p, LAS unsigned char* lds) {
;     ...
;     for (int u = bx; u < 1024; u += G) {
;         const int tt = u >> 2, g = u & 3, b = tt >> 5, t0 = (tt & 31) * 64, grow0 = b * T + t0, w = 2 << g;
;         POOL_LOADW(g);
;         u32x4 cp[3];
; #pragma unroll
;         for (int i = 0; i < 3; ++i) cp[i] = pq[i];
;         if (u + G < 1024) POOL_PREFETCH(u + G);
; #pragma unroll
;         for (int i = 0; i < 3; ++i) { const int o = tid + 512 * i, rr = o >> 4, c8 = (o & 15) * 8;
;             if (o < 79 * 16) { const u32x4 q = cp[i];
;                 *(LAS f32x4*)(P + rr * 128 + c8) = (f32x4){bflo(q.x), bfhi(q.x), bflo(q.y), bfhi(q.y)}; *(LAS f32x4*)(P + rr * 128 + c8 + 4) = (f32x4){bflo(q.z), bfhi(q.z), bflo(q.w), bfhi(q.w)}; } }
;         LDS_BARRIER();
;         { const int c = tid & 127, tl0 = (tid >> 7) * 16; const float invw = 1.0f / (float)w;
;             float S = 0.f;
;             for (int j = 1; j < w; ++j) S += P[(tl0 + 15 - j) * 128 + c];
; #pragma unroll 4
;             for (int i = 0; i < 16; ++i) { const int tl = tl0 + i; const float cur = P[(tl + 15) * 128 + c]; S += cur;
;                 const int pos = t0 + tl; const float inv = (pos + 1 >= w) ? invw : __builtin_amdgcn_rcpf((float)(pos + 1));
;                 Dm[tl * 136 + c] = f2bf(S * inv - cur);
;                 S -= P[(tl + 16 - w) * 128 + c]; }
;         }
.LBB0_287:
	s_cmp_eq_u32 s101, 2
	s_cbranch_scc1 .LBB0_333
	v_lshrrev_b32_e32 v14, 4, v90
	v_and_b32_e32 v107, 15, v0
	s_and_b32 s52, s10, 3
	s_ashr_i32 s54, s10, 2
	s_andn2_b64 vcc, exec, s[4:5]
	v_lshlrev_b32_e32 v133, 1, v0
	v_and_b32_e32 v109, 3, v0
	v_lshlrev_b32_e32 v110, 3, v14
	v_lshlrev_b32_e32 v114, 5, v14
	v_lshlrev_b32_e32 v112, 4, v14
	s_cbranch_vccnz .LBB0_320
	s_mov_b32 s99, 0
	s_lshl_b32 s68, s54, 6
	v_and_b32_e32 v14, 24, v133
	v_lshlrev_b32_e32 v18, 3, v0
	v_and_b32_e32 v15, 0x78, v18
	v_or3_b32 v14, v14, v109, s68
	v_lshlrev_b32_e32 v116, 1, v15
	v_lshl_add_u32 v19, v15, 2, 0
	v_lshrrev_b32_e32 v15, 3, v0
	v_or_b32_e32 v16, 4, v14
	v_and_b32_e32 v138, 48, v15
	v_lshlrev_b32_e32 v21, 9, v15
	v_ashrrev_i32_e32 v15, 31, v14
	v_ashrrev_i32_e32 v17, 31, v16
	v_lshlrev_b64 v[120:121], 8, v[14:15]
	v_lshlrev_b64 v[122:123], 8, v[16:17]
	v_or_b32_e32 v16, 32, v14
	v_or_b32_e32 v14, 36, v14
	v_ashrrev_i32_e32 v15, 31, v14
	s_load_dwordx16 s[36:51], s[0:1], 0x40
	v_lshlrev_b64 v[126:127], 8, v[14:15]
	v_lshlrev_b32_e32 v15, 5, v0
	v_and_b32_e32 v15, 0x3e00, v15
	s_ashr_i32 s69, s68, 31
	v_or_b32_e32 v14, 0x200, v0
	v_add_u32_e32 v142, v19, v15
	s_movk_i32 s8, 0x1f80
	v_mov_b32_e32 v15, 0x1000
	v_lshrrev_b32_e32 v140, 4, v14
	v_or_b32_e32 v14, 0x400, v0
	s_movk_i32 s6, 0x4f0
	v_bitop3_b32 v15, v18, s8, v15 bitop3:0xc8
	s_lshl_b64 s[8:9], s[68:69], 2
	v_mov_b32_e32 v117, 0
	v_cmp_gt_u32_e64 s[6:7], s6, v14
	v_lshrrev_b32_e32 v141, 4, v14
	v_lshlrev_b32_e32 v14, 5, v14
	s_waitcnt lgkmcnt(0)
	s_add_u32 s8, s38, s8
	v_and_b32_e32 v14, 0xbe00, v14
	s_addc_u32 s9, s39, s9
	v_mov_b32_e32 v115, v117
	v_mov_b32_e32 v113, v117
	v_and_b32_e32 v20, 0x7f, v0
	v_lshl_add_u32 v143, v15, 2, v19
	v_add_u32_e32 v144, v19, v14
	v_lshl_add_u64 v[128:129], s[8:9], 0, v[114:115]
	v_lshl_add_u64 v[14:15], s[30:31], 0, v[112:113]
	s_mov_b64 s[8:9], 0x2d00000
	v_lshl_add_u64 v[118:119], s[64:65], 0, v[116:117]
	v_lshl_add_u64 v[130:131], v[14:15], 0, s[8:9]
	v_lshlrev_b32_e32 v116, 2, v20
	s_movk_i32 s8, 0x1e00
	v_or3_b32 v14, v21, v116, s8
	v_lshrrev_b32_e32 v132, 7, v0
	v_add_u32_e32 v113, 0, v14
	v_lshl_or_b32 v14, v132, 13, v116
	v_add_u32_e32 v14, 0, v14
	v_add_u32_e32 v145, 0x1e00, v14
	v_mul_u32_u24_e32 v14, 0x1100, v132
	v_lshl_or_b32 v14, v20, 1, v14
	v_add_u32_e32 v14, 0, v14
	v_lshl_or_b32 v139, s52, 4, v107
	s_movk_i32 s4, 0x110
	v_add_u32_e32 v146, 0x9e00, v14
	v_lshl_add_u32 v14, v0, 2, 0
	v_mad_u32_u24 v22, v139, s4, 0
	v_and_b32_e32 v23, 48, v0
	v_ashrrev_i32_e32 v17, 31, v16
	s_movk_i32 s4, 0x2f0
	v_add_u32_e32 v148, 0x8000, v14
	v_lshl_add_u64 v[14:15], s[28:29], 0, v[116:117]
	s_mov_b64 s[8:9], 0x4080000
	s_mov_b32 s71, 0
	v_lshlrev_b64 v[124:125], 8, v[16:17]
	v_cmp_gt_u32_e64 s[4:5], s4, v0
	v_add_u32_e32 v115, 0xfffff000, v113
	s_lshl_b32 s55, s2, 4
	s_lshl_b32 s56, s3, 4
	v_or_b32_e32 v147, 0xfffffe00, v0
	v_lshl_add_u64 v[134:135], v[14:15], 0, s[8:9]
	s_mov_b32 s53, -1
	s_movk_i32 s57, 0x7fff
	s_mov_b64 s[72:73], 0x2000
	s_movk_i32 s58, 0x57f
	v_add_u32_e32 v149, v22, v23
	v_lshlrev_b32_e32 v116, 1, v110
	s_mov_b32 s59, s2
	s_mov_b32 s77, s2
	s_and_b32 s78, s77, 3
	s_cmp_eq_u32 s78, s53
	s_cbranch_scc1 .LBB0_291
	s_branch .LBB0_290

; #define LDS_BARRIER() do { asm volatile("s_waitcnt lgkmcnt(0)" ::: "memory"); __builtin_amdgcn_s_barrier(); asm volatile("" ::: "memory"); } while (0)
; __device__ __forceinline__ void mixer_phase(const Params& p, LAS unsigned char* lds) {
;     ...
;         LDS_BARRIER();
;         POOL_MMA_STORE(g, grow0);
;     }
.LBB0_318:
	s_waitcnt lgkmcnt(0)
	s_barrier
	ds_read_b128 v[2:5], v149 offset:40448
	ds_read_b128 v[6:9], v149 offset:40512
	v_lshl_or_b32 v136, s11, 11, v139
	s_waitcnt lgkmcnt(1)
	v_mfma_f32_16x16x32_bf16 v[10:13], v[70:73], v[2:5], 0
	v_or_b32_e32 v136, s10, v136
	v_ashrrev_i32_e32 v137, 31, v136
	v_lshlrev_b64 v[136:137], 11, v[136:137]
	v_mfma_f32_16x16x32_bf16 v[150:153], v[74:77], v[2:5], 0
	v_lshl_add_u64 v[136:137], s[66:67], 0, v[136:137]
	v_lshl_add_u64 v[136:137], s[70:71], 1, v[136:137]
	v_lshl_add_u64 v[136:137], s[68:69], 1, v[136:137]
	v_mfma_f32_16x16x32_bf16 v[154:157], v[66:69], v[2:5], 0
	v_lshl_add_u64 v[136:137], v[136:137], 0, v[116:117]
	s_lshl_b32 s55, s76, 4
	s_mov_b32 s59, s76
	v_mfma_f32_16x16x32_bf16 v[2:5], v[62:65], v[2:5], 0
	s_and_b64 vcc, exec, s[74:75]
	s_waitcnt lgkmcnt(0)
	v_mfma_f32_16x16x32_bf16 v[10:13], v[58:61], v[6:9], v[10:13]
	v_mfma_f32_16x16x32_bf16 v[150:153], v[54:57], v[6:9], v[150:153]
	v_mfma_f32_16x16x32_bf16 v[154:157], v[50:53], v[6:9], v[154:157]
	v_mfma_f32_16x16x32_bf16 v[2:5], v[42:45], v[6:9], v[2:5]
	ds_read_b128 v[6:9], v149 offset:40576
	ds_read_b128 v[158:161], v149 offset:40640
	s_waitcnt lgkmcnt(1)
	v_mfma_f32_16x16x32_bf16 v[10:13], v[30:33], v[6:9], v[10:13]
	v_mfma_f32_16x16x32_bf16 v[150:153], v[46:49], v[6:9], v[150:153]
	s_waitcnt lgkmcnt(0)
	v_mfma_f32_16x16x32_bf16 v[10:13], v[26:29], v[158:161], v[10:13]
	v_mfma_f32_16x16x32_bf16 v[154:157], v[38:41], v[6:9], v[154:157]
	v_mfma_f32_16x16x32_bf16 v[150:153], v[22:25], v[158:161], v[150:153]
	s_nop 5
	v_mul_f32_e64 v12, v84, v12
	v_mul_f32_e64 v13, v85, v13
	v_pk_mul_f32 v[10:11], v[82:83], v[10:11]
	v_mfma_f32_16x16x32_bf16 v[2:5], v[34:37], v[6:9], v[2:5]
	v_cvt_pk_bf16_f32 v10, v10, v11
	v_cvt_pk_bf16_f32 v11, v12, v13
	v_mul_f32_e64 v162, v80, v152
	v_mul_f32_e64 v163, v81, v153
	v_pk_mul_f32 v[12:13], v[78:79], v[150:151]
	v_mfma_f32_16x16x32_bf16 v[150:153], v[18:21], v[158:161], v[154:157]
	v_cvt_pk_bf16_f32 v12, v12, v13
	v_cvt_pk_bf16_f32 v13, v162, v163
	global_store_dwordx4 v[136:137], v[10:13], off
	v_mfma_f32_16x16x32_bf16 v[2:5], v[14:17], v[158:161], v[2:5]
	s_nop 5
	v_mul_f32_e64 v6, v90, v150
	v_mul_f32_e64 v7, v91, v151
	v_pk_mul_f32 v[10:11], v[92:93], v[152:153]
	v_cvt_pk_bf16_f32 v6, v6, v7
	v_pk_mul_f32 v[4:5], v[88:89], v[4:5]
	v_cvt_pk_bf16_f32 v7, v10, v11
	v_pk_mul_f32 v[2:3], v[86:87], v[2:3]
	v_cvt_pk_bf16_f32 v9, v4, v5
	s_nop 0
	v_cvt_pk_bf16_f32 v8, v2, v3
	global_store_dwordx4 v[136:137], v[6:9], off offset:64
	s_cbranch_vccz .LBB0_289
	s_cmp_eq_u32 s101, 1
	s_cbranch_scc0 .Lmy_p2noswap
	s_mov_b32 s101, 2
	s_branch .Lmy_conv_body
.Lmy_p2noswap:
	s_cmp_gt_i32 s2, 47
	s_cbranch_scc1 .LBB0_333
	s_branch .LBB0_321
